# local attention S-part: bias reads use two base registers + ds_read2 immediate offsets, redundant waits and padding nops removed (hazard distances re-derived by checker)
# speedup vs baseline: 1.0127x; 1.0103x over previous
; #define LAS __attribute__((address_space(3)))
; __device__ __forceinline__ int kswz(int key) { return ((key >> 1) & 1) | (((key >> 3) & 3) << 1); }
; #define AH_LDK(c, bufi) do { kf[bufi][0] = *(const LAS bf16x8*)(lds + kaddr0 + (c) * kcs); kf[bufi][1] = *(const LAS bf16x8*)(lds + kaddr1 + (c) * kcs); \
;         kf[bufi][2] = *(const LAS bf16x8*)(lds + kaddr0 + (c) * kcs + 512); kf[bufi][3] = *(const LAS bf16x8*)(lds + kaddr1 + (c) * kcs + 512); } while (0)
; template <bool LOC> ...
;     ...
;     for (int c = 0; c < 8; ++c) {
;         if (c < 7) AH_LDK(c + 1, (c + 1) & 1);
;         __builtin_amdgcn_sched_barrier(0);
;         f32x4 t0 = (f32x4){0.f, 0.f, 0.f, 0.f}, t1 = (f32x4){0.f, 0.f, 0.f, 0.f};
;         t0 = __builtin_amdgcn_mfma_f32_16x16x32_bf16(kf[c & 1][0], q0, t0, 0, 0, 0); t1 = __builtin_amdgcn_mfma_f32_16x16x32_bf16(kf[c & 1][2], q0, t1, 0, 0, 0);
;         t0 = __builtin_amdgcn_mfma_f32_16x16x32_bf16(kf[c & 1][1], q1, t0, 0, 0, 0); t1 = __builtin_amdgcn_mfma_f32_16x16x32_bf16(kf[c & 1][3], q1, t1, 0, 0, 0);
; #pragma unroll
;         for (int e = 0; e < 8; ++e) { const float a = (e < 4) ? t0[e] : t1[e - 4];
;             if (LOC) { const float bv = bp[c * RPB_PITCH + e]; const bool ok = (e >= elo) && (e < elo + 16); s[c][e] = ok ? (a * SC + bv) : -INFINITY; }
;             else s[c][e] = a * SC; }
;         __builtin_amdgcn_sched_barrier(0);
;     }
; __device__ __forceinline__ void phase_mixer(const Params& p, LAS unsigned char* lds, int l, bool with_ctx, int G, int tid, int wave, int lane, int rep_attn, int rep_pool) {
;     ...
;             const int kl = (rs - rs0) * 64 + kc0 + kap, ka0 = AT_KL + kl * 128 + ((g ^ kswz(kl)) << 4), ka1 = AT_KL + kl * 128 + (((g + 4) ^ kswz(kl)) << 4);
;             const int vrow = AT_VL + qi * AT_VLP, vch0 = (rs - rs0) * 8 + (kc0 >> 3);
;             const LAS float* bp = (const LAS float*)(lds + AT_RPB) + (rs - r + 7) * RPB_PITCH + RPB_OFF + (kc0 + 8 * g - qc + 15);
;             attn_half<true>(lds, ka0, ka1, 64 * 128, vrow, vch0, 8, 16 * AT_VLP, bp, qs - kc0 - 8 * g, qA0, qA1, mxA, lA, oA, g, qi);
.LBB0_296:
	s_or_b64 exec, exec, s[68:69]
	s_add_i32 s64, s64, -4
	s_min_u32 s64, s64, 56
	v_sub_u32_e32 v36, s64, v26
	v_lshl_add_u32 v24, v36, 13, v128
	v_add_u32_e32 v25, v24, v126
	s_waitcnt lgkmcnt(0)
	s_barrier
	v_add_u32_e32 v26, v24, v127
	ds_read_b128 v[30:33], v25
	ds_read_b128 v[38:41], v25 offset:512
	ds_read_b128 v[42:45], v26
	ds_read_b128 v[46:49], v26 offset:512
	ds_read_b128 v[50:53], v25 offset:8192
	ds_read_b128 v[54:57], v25 offset:8704
	ds_read_b128 v[58:61], v26 offset:8192
	ds_read_b128 v[62:65], v26 offset:8704
	s_sub_i32 s63, s64, s63
	v_lshl_add_u32 v24, s63, 8, v129
	v_add_u32_e32 v235, 0x77c, v24
	v_add_u32_e32 v236, 0xb7c, v24
	s_waitcnt lgkmcnt(7)
	v_mfma_f32_16x16x32_bf16 v[30:33], v[30:33], v[4:7], 0
	ds_read2_b32 v[34:35], v235 offset0:0 offset1:1
	s_waitcnt lgkmcnt(6)
	v_mfma_f32_16x16x32_bf16 v[30:33], v[42:45], v[0:3], v[30:33]
	v_mfma_f32_16x16x32_bf16 v[38:41], v[38:41], v[4:7], 0
	s_waitcnt lgkmcnt(5)
	v_mfma_f32_16x16x32_bf16 v[38:41], v[46:49], v[0:3], v[38:41]
	ds_read2_b32 v[238:239], v235 offset0:2 offset1:3
	ds_read2_b32 v[240:241], v235 offset0:4 offset1:5
	ds_read2_b32 v[242:243], v235 offset0:6 offset1:7
	s_waitcnt lgkmcnt(0)
	s_nop 3
	v_fmamk_f32 v27, v30, 0x3e38aa3b, v34
	v_cndmask_b32_e64 v30, v222, v27, s[6:7]
	v_fmac_f32_e32 v35, 0x3e38aa3b, v31
	v_cndmask_b32_e64 v29, v222, v35, s[8:9]
	v_fmamk_f32 v27, v32, 0x3e38aa3b, v238
	v_cndmask_b32_e64 v32, v222, v27, s[10:11]
	v_fmac_f32_e32 v239, 0x3e38aa3b, v33
	v_cndmask_b32_e64 v31, v222, v239, s[12:13]
	v_fmamk_f32 v27, v38, 0x3e38aa3b, v240
	v_cndmask_b32_e64 v34, v222, v27, s[14:15]
	v_fmac_f32_e32 v241, 0x3e38aa3b, v39
	v_cndmask_b32_e64 v33, v222, v241, s[16:17]
	v_fmamk_f32 v27, v40, 0x3e38aa3b, v242
	v_fmac_f32_e32 v243, 0x3e38aa3b, v41
	v_cndmask_b32_e64 v43, v222, v27, s[18:19]
	v_cndmask_b32_e64 v41, v222, v243, s[20:21]
	ds_read_b128 v[44:47], v25 offset:16384
	ds_read_b128 v[66:69], v25 offset:16896
	ds_read_b128 v[100:103], v26 offset:16384
	ds_read_b128 v[152:155], v26 offset:16896
	v_mfma_f32_16x16x32_bf16 v[48:51], v[50:53], v[4:7], 0
	ds_read2_b32 v[38:39], v235 offset0:64 offset1:65
	v_mfma_f32_16x16x32_bf16 v[48:51], v[58:61], v[0:3], v[48:51]
	v_mfma_f32_16x16x32_bf16 v[52:55], v[54:57], v[4:7], 0
	v_mfma_f32_16x16x32_bf16 v[52:55], v[62:65], v[0:3], v[52:55]
	ds_read2_b32 v[238:239], v235 offset0:66 offset1:67
	ds_read2_b32 v[240:241], v235 offset0:68 offset1:69
	ds_read2_b32 v[242:243], v235 offset0:70 offset1:71
	s_waitcnt lgkmcnt(0)
	s_nop 4
	v_fmamk_f32 v27, v48, 0x3e38aa3b, v38
	v_cndmask_b32_e64 v37, v222, v27, s[6:7]
	v_fmac_f32_e32 v39, 0x3e38aa3b, v49
	v_cndmask_b32_e64 v35, v222, v39, s[8:9]
	v_fmamk_f32 v27, v50, 0x3e38aa3b, v238
	v_cndmask_b32_e64 v39, v222, v27, s[10:11]
	v_fmac_f32_e32 v239, 0x3e38aa3b, v51
	v_cndmask_b32_e64 v38, v222, v239, s[12:13]
	v_fmamk_f32 v27, v52, 0x3e38aa3b, v240
	v_cndmask_b32_e64 v42, v222, v27, s[14:15]
	v_fmac_f32_e32 v241, 0x3e38aa3b, v53
	v_cndmask_b32_e64 v40, v222, v241, s[16:17]
	v_fmamk_f32 v27, v54, 0x3e38aa3b, v242
	v_fmac_f32_e32 v243, 0x3e38aa3b, v55
	v_cndmask_b32_e64 v51, v222, v27, s[18:19]
	v_cndmask_b32_e64 v49, v222, v243, s[20:21]
	ds_read_b128 v[52:55], v25 offset:24576
	ds_read_b128 v[60:63], v25 offset:25088
	ds_read_b128 v[170:173], v26 offset:24576
	ds_read_b128 v[174:177], v26 offset:25088
	v_mfma_f32_16x16x32_bf16 v[44:47], v[44:47], v[4:7], 0
	v_mfma_f32_16x16x32_bf16 v[56:59], v[66:69], v[4:7], 0
	v_mfma_f32_16x16x32_bf16 v[64:67], v[100:103], v[0:3], v[44:47]
	s_nop 4
	ds_read2_b32 v[46:47], v235 offset0:128 offset1:129
	v_mfma_f32_16x16x32_bf16 v[68:71], v[152:155], v[0:3], v[56:59]
	ds_read2_b32 v[238:239], v235 offset0:130 offset1:131
	ds_read2_b32 v[240:241], v235 offset0:132 offset1:133
	ds_read2_b32 v[242:243], v235 offset0:134 offset1:135
	s_waitcnt lgkmcnt(0)
	v_fmamk_f32 v27, v64, 0x3e38aa3b, v46
	v_cndmask_b32_e64 v45, v222, v27, s[6:7]
	v_fmac_f32_e32 v47, 0x3e38aa3b, v65
	v_cndmask_b32_e64 v44, v222, v47, s[8:9]
	v_fmamk_f32 v27, v66, 0x3e38aa3b, v238
	v_cndmask_b32_e64 v47, v222, v27, s[10:11]
	v_fmac_f32_e32 v239, 0x3e38aa3b, v67
	v_cndmask_b32_e64 v46, v222, v239, s[12:13]
	v_fmamk_f32 v27, v68, 0x3e38aa3b, v240
	v_cndmask_b32_e64 v50, v222, v27, s[14:15]
	v_fmac_f32_e32 v241, 0x3e38aa3b, v69
	v_cndmask_b32_e64 v48, v222, v241, s[16:17]
	v_fmamk_f32 v27, v70, 0x3e38aa3b, v242
	v_fmac_f32_e32 v243, 0x3e38aa3b, v71
	v_cndmask_b32_e64 v59, v222, v27, s[18:19]
	v_cndmask_b32_e64 v57, v222, v243, s[20:21]
	ds_read_b128 v[68:71], v25 offset:32768
	ds_read_b128 v[100:103], v25 offset:33280
	ds_read_b128 v[152:155], v26 offset:32768
	ds_read_b128 v[178:181], v26 offset:33280
	v_mfma_f32_16x16x32_bf16 v[52:55], v[52:55], v[4:7], 0
	v_mfma_f32_16x16x32_bf16 v[64:67], v[170:173], v[0:3], v[52:55]
	v_mfma_f32_16x16x32_bf16 v[60:63], v[60:63], v[4:7], 0
	s_nop 4
	ds_read2_b32 v[54:55], v235 offset0:192 offset1:193
	ds_read2_b32 v[238:239], v235 offset0:194 offset1:195
	ds_read2_b32 v[240:241], v235 offset0:196 offset1:197
	ds_read2_b32 v[242:243], v235 offset0:198 offset1:199
	s_waitcnt lgkmcnt(0)
; #define AH_LDK(c, bufi) do { kf[bufi][0] = *(const LAS bf16x8*)(lds + kaddr0 + (c) * kcs); kf[bufi][1] = *(const LAS bf16x8*)(lds + kaddr1 + (c) * kcs); \
;         kf[bufi][2] = *(const LAS bf16x8*)(lds + kaddr0 + (c) * kcs + 512); kf[bufi][3] = *(const LAS bf16x8*)(lds + kaddr1 + (c) * kcs + 512); } while (0)
; template <bool LOC> ...
;     ...
;     for (int c = 0; c < 8; ++c) {
;         if (c < 7) AH_LDK(c + 1, (c + 1) & 1);
;         __builtin_amdgcn_sched_barrier(0);
;         f32x4 t0 = (f32x4){0.f, 0.f, 0.f, 0.f}, t1 = (f32x4){0.f, 0.f, 0.f, 0.f};
;         t0 = __builtin_amdgcn_mfma_f32_16x16x32_bf16(kf[c & 1][0], q0, t0, 0, 0, 0); t1 = __builtin_amdgcn_mfma_f32_16x16x32_bf16(kf[c & 1][2], q0, t1, 0, 0, 0);
;         t0 = __builtin_amdgcn_mfma_f32_16x16x32_bf16(kf[c & 1][1], q1, t0, 0, 0, 0); t1 = __builtin_amdgcn_mfma_f32_16x16x32_bf16(kf[c & 1][3], q1, t1, 0, 0, 0);
; #pragma unroll
;         for (int e = 0; e < 8; ++e) { const float a = (e < 4) ? t0[e] : t1[e - 4];
;             if (LOC) { const float bv = bp[c * RPB_PITCH + e]; const bool ok = (e >= elo) && (e < elo + 16); s[c][e] = ok ? (a * SC + bv) : -INFINITY; }
;             else s[c][e] = a * SC; }
;         __builtin_amdgcn_sched_barrier(0);
;     }
	v_fmamk_f32 v27, v64, 0x3e38aa3b, v54
	v_cndmask_b32_e64 v53, v222, v27, s[6:7]
	v_fmac_f32_e32 v55, 0x3e38aa3b, v65
	v_cndmask_b32_e64 v52, v222, v55, s[8:9]
	v_mfma_f32_16x16x32_bf16 v[60:63], v[174:177], v[0:3], v[60:63]
	v_fmamk_f32 v27, v66, 0x3e38aa3b, v238
	v_cndmask_b32_e64 v55, v222, v27, s[10:11]
	v_fmac_f32_e32 v239, 0x3e38aa3b, v67
	v_cndmask_b32_e64 v54, v222, v239, s[12:13]
	s_nop 3
	v_fmamk_f32 v27, v60, 0x3e38aa3b, v240
	v_cndmask_b32_e64 v58, v222, v27, s[14:15]
	v_fmac_f32_e32 v241, 0x3e38aa3b, v61
	v_cndmask_b32_e64 v56, v222, v241, s[16:17]
	v_fmamk_f32 v27, v62, 0x3e38aa3b, v242
	v_fmac_f32_e32 v243, 0x3e38aa3b, v63
	v_cndmask_b32_e64 v67, v222, v27, s[18:19]
	v_cndmask_b32_e64 v65, v222, v243, s[20:21]
	ds_read_b128 v[170:173], v25 offset:40960
	ds_read_b128 v[174:177], v25 offset:41472
	ds_read_b128 v[182:185], v26 offset:40960
	ds_read_b128 v[186:189], v26 offset:41472
	v_mfma_f32_16x16x32_bf16 v[60:63], v[68:71], v[4:7], 0
	v_mfma_f32_16x16x32_bf16 v[68:71], v[100:103], v[4:7], 0
	v_mfma_f32_16x16x32_bf16 v[100:103], v[152:155], v[0:3], v[60:63]
	s_nop 4
	ds_read2_b32 v[62:63], v236 offset0:0 offset1:1
	v_mfma_f32_16x16x32_bf16 v[68:71], v[178:181], v[0:3], v[68:71]
	ds_read2_b32 v[238:239], v236 offset0:2 offset1:3
	ds_read2_b32 v[240:241], v236 offset0:4 offset1:5
	ds_read2_b32 v[242:243], v236 offset0:6 offset1:7
	s_waitcnt lgkmcnt(0)
	v_fmamk_f32 v27, v100, 0x3e38aa3b, v62
	v_cndmask_b32_e64 v61, v222, v27, s[6:7]
	v_fmac_f32_e32 v63, 0x3e38aa3b, v101
	v_cndmask_b32_e64 v60, v222, v63, s[8:9]
	v_fmamk_f32 v27, v102, 0x3e38aa3b, v238
	v_cndmask_b32_e64 v63, v222, v27, s[10:11]
	v_fmac_f32_e32 v239, 0x3e38aa3b, v103
	v_cndmask_b32_e64 v62, v222, v239, s[12:13]
	v_fmamk_f32 v27, v68, 0x3e38aa3b, v240
	v_cndmask_b32_e64 v66, v222, v27, s[14:15]
	v_fmac_f32_e32 v241, 0x3e38aa3b, v69
	v_cndmask_b32_e64 v64, v222, v241, s[16:17]
	v_fmamk_f32 v27, v70, 0x3e38aa3b, v242
	v_fmac_f32_e32 v243, 0x3e38aa3b, v71
	v_cndmask_b32_e64 v102, v222, v27, s[18:19]
	v_cndmask_b32_e64 v100, v222, v243, s[20:21]
	ds_read_b128 v[178:181], v25 offset:49152
	ds_read_b128 v[190:193], v25 offset:49664
	ds_read_b128 v[194:197], v26 offset:49152
	ds_read_b128 v[198:201], v26 offset:49664
	v_mfma_f32_16x16x32_bf16 v[68:71], v[170:173], v[4:7], 0
	v_mfma_f32_16x16x32_bf16 v[170:173], v[182:185], v[0:3], v[68:71]
	v_mfma_f32_16x16x32_bf16 v[152:155], v[174:177], v[4:7], 0
	s_nop 4
	ds_read2_b32 v[70:71], v236 offset0:64 offset1:65
	ds_read2_b32 v[238:239], v236 offset0:66 offset1:67
	ds_read2_b32 v[240:241], v236 offset0:68 offset1:69
	ds_read2_b32 v[242:243], v236 offset0:70 offset1:71
	s_waitcnt lgkmcnt(0)
	v_fmamk_f32 v27, v170, 0x3e38aa3b, v70
	v_cndmask_b32_e64 v69, v222, v27, s[6:7]
	v_fmac_f32_e32 v71, 0x3e38aa3b, v171
	v_cndmask_b32_e64 v68, v222, v71, s[8:9]
	v_mfma_f32_16x16x32_bf16 v[174:177], v[186:189], v[0:3], v[152:155]
	v_fmamk_f32 v27, v172, 0x3e38aa3b, v238
	v_cndmask_b32_e64 v71, v222, v27, s[10:11]
	v_fmac_f32_e32 v239, 0x3e38aa3b, v173
	v_cndmask_b32_e64 v70, v222, v239, s[12:13]
	s_nop 3
	v_fmamk_f32 v27, v174, 0x3e38aa3b, v240
	v_cndmask_b32_e64 v101, v222, v27, s[14:15]
	v_fmac_f32_e32 v241, 0x3e38aa3b, v175
	v_cndmask_b32_e64 v99, v222, v241, s[16:17]
	v_fmamk_f32 v27, v176, 0x3e38aa3b, v242
	v_fmac_f32_e32 v243, 0x3e38aa3b, v177
	v_cndmask_b32_e64 v155, v222, v27, s[18:19]
	v_cndmask_b32_e64 v153, v222, v243, s[20:21]
	ds_read_b128 v[182:185], v25 offset:57344
	ds_read_b128 v[186:189], v25 offset:57856
	ds_read_b128 v[202:205], v26 offset:57344
	ds_read_b128 v[206:209], v26 offset:57856
	v_mfma_f32_16x16x32_bf16 v[170:173], v[178:181], v[4:7], 0
	ds_read2_b32 v[26:27], v236 offset0:128 offset1:129
	v_mfma_f32_16x16x32_bf16 v[170:173], v[194:197], v[0:3], v[170:173]
	v_mfma_f32_16x16x32_bf16 v[174:177], v[190:193], v[4:7], 0
	v_mfma_f32_16x16x32_bf16 v[174:177], v[198:201], v[0:3], v[174:177]
	ds_read2_b32 v[238:239], v236 offset0:130 offset1:131
	ds_read2_b32 v[240:241], v236 offset0:132 offset1:133
	ds_read2_b32 v[242:243], v236 offset0:134 offset1:135
	s_waitcnt lgkmcnt(0)
	s_nop 4
	v_fmamk_f32 v25, v170, 0x3e38aa3b, v26
	v_cndmask_b32_e64 v104, v222, v25, s[6:7]
	v_fmac_f32_e32 v27, 0x3e38aa3b, v171
	v_cndmask_b32_e64 v103, v222, v27, s[8:9]
	v_fmamk_f32 v25, v172, 0x3e38aa3b, v238
	v_cndmask_b32_e64 v151, v222, v25, s[10:11]
	v_fmac_f32_e32 v239, 0x3e38aa3b, v173
	v_cndmask_b32_e64 v105, v222, v239, s[12:13]
	v_fmamk_f32 v25, v174, 0x3e38aa3b, v240
	v_cndmask_b32_e64 v154, v222, v25, s[14:15]
	v_fmac_f32_e32 v241, 0x3e38aa3b, v175
	v_cndmask_b32_e64 v152, v222, v241, s[16:17]
	v_fmamk_f32 v25, v176, 0x3e38aa3b, v242
	v_fmac_f32_e32 v243, 0x3e38aa3b, v177
	v_cndmask_b32_e64 v175, v222, v25, s[18:19]
	v_cndmask_b32_e64 v173, v222, v243, s[20:21]
	v_mfma_f32_16x16x32_bf16 v[176:179], v[182:185], v[4:7], 0
	v_mfma_f32_16x16x32_bf16 v[4:7], v[186:189], v[4:7], 0
	v_mfma_f32_16x16x32_bf16 v[176:179], v[202:205], v[0:3], v[176:179]
	v_mfma_f32_16x16x32_bf16 v[0:3], v[206:209], v[0:3], v[4:7]
	s_nop 5
	ds_read2_b32 v[4:5], v236 offset0:192 offset1:193
	ds_read2_b32 v[238:239], v236 offset0:194 offset1:195
	ds_read2_b32 v[240:241], v236 offset0:196 offset1:197
	ds_read2_b32 v[242:243], v236 offset0:198 offset1:199
	s_waitcnt lgkmcnt(0)
; __device__ __forceinline__ unsigned cvt_pk_bf16(float lo, float hi) { const f32x2 v = (f32x2){lo, hi}; return __builtin_bit_cast(unsigned, __builtin_convertvector(v, bf16v2)); }
; #define AH_LDV(c, bufi) do { const int vaddr = vrow + (((vchunk0 + (c) * vcs + g) ^ qi) << 4); _Pragma("unroll") for (int dt = 0; dt < 4; ++dt) vf[bufi][dt] = *(const LAS bf16x8*)(lds + vaddr + dt * vpitch_dt); } while (0)
; template <bool LOC> ...
;     ...
;     float m2 = mx;
; #pragma unroll
;     for (int c = 0; c < 8; ++c)
; #pragma unroll
;         for (int e = 0; e < 8; ++e) m2 = fmaxf(m2, s[c][e]);
;     m2 = fmaxf(m2, __shfl_xor(m2, 16)); m2 = fmaxf(m2, __shfl_xor(m2, 32));
;     const float alpha = __builtin_amdgcn_exp2f(mx - m2);
;     mx = m2; lsum *= alpha;
; #pragma unroll
;     for (int dt = 0; dt < 4; ++dt) o[dt] = o[dt] * alpha;
;     bf16x8 vf[2][4];
;     ...
;     AH_LDV(0, 0);
; #pragma unroll
;     for (int c = 0; c < 8; ++c) {
;         if (c < 7) AH_LDV(c + 1, (c + 1) & 1);
;         __builtin_amdgcn_sched_barrier(0);
;         float pe[8];
; #pragma unroll
;         for (int e = 0; e < 8; ++e) { pe[e] = __builtin_amdgcn_exp2f(s[c][e] - mx); lsum += pe[e]; }
;         u32x4 pw; pw.x = cvt_pk_bf16(pe[0], pe[1]); pw.y = cvt_pk_bf16(pe[2], pe[3]); pw.z = cvt_pk_bf16(pe[4], pe[5]); pw.w = cvt_pk_bf16(pe[6], pe[7]);
;         const bf16x8 pb = __builtin_bit_cast(bf16x8, pw);
; #pragma unroll
;         for (int dt = 0; dt < 4; ++dt) o[dt] = __builtin_amdgcn_mfma_f32_16x16x32_bf16(vf[c & 1][dt], pb, o[dt], 0, 0, 0);
;         __builtin_amdgcn_sched_barrier(0);
;     }
	v_fmamk_f32 v4, v176, 0x3e38aa3b, v4
	v_cndmask_b32_e64 v170, v222, v4, s[6:7]
	v_fmac_f32_e32 v5, 0x3e38aa3b, v177
	v_cndmask_b32_e64 v167, v222, v5, s[8:9]
	v_fmamk_f32 v4, v178, 0x3e38aa3b, v238
	v_cndmask_b32_e64 v172, v222, v4, s[10:11]
	v_fmac_f32_e32 v239, 0x3e38aa3b, v179
	v_cndmask_b32_e64 v171, v222, v239, s[12:13]
	v_fmamk_f32 v0, v0, 0x3e38aa3b, v240
	v_cndmask_b32_e64 v176, v222, v0, s[14:15]
	v_fmac_f32_e32 v241, 0x3e38aa3b, v1
	v_cndmask_b32_e64 v174, v222, v241, s[16:17]
	v_fmamk_f32 v0, v2, 0x3e38aa3b, v242
	v_fmac_f32_e32 v243, 0x3e38aa3b, v3
	v_cndmask_b32_e64 v178, v222, v0, s[18:19]
	v_cndmask_b32_e64 v177, v222, v243, s[20:21]
	v_max3_f32 v0, v97, v30, v29
	v_max3_f32 v0, v0, v32, v31
	v_max3_f32 v0, v0, v34, v33
	v_max3_f32 v0, v0, v43, v41
	v_max3_f32 v0, v0, v37, v35
	v_max3_f32 v0, v0, v39, v38
	v_max3_f32 v0, v0, v42, v40
	v_max3_f32 v0, v0, v51, v49
	v_max3_f32 v0, v0, v45, v44
	v_max3_f32 v0, v0, v47, v46
	v_max3_f32 v0, v0, v50, v48
	v_max3_f32 v0, v0, v59, v57
	v_max3_f32 v0, v0, v53, v52
	v_max3_f32 v0, v0, v55, v54
	v_max3_f32 v0, v0, v58, v56
	v_max3_f32 v0, v0, v67, v65
	v_max3_f32 v0, v0, v61, v60
	v_max3_f32 v0, v0, v63, v62
	v_max3_f32 v0, v0, v66, v64
	v_max3_f32 v0, v0, v102, v100
	v_max3_f32 v0, v0, v69, v68
	v_max3_f32 v0, v0, v71, v70
	v_max3_f32 v0, v0, v101, v99
	v_max3_f32 v0, v0, v155, v153
	v_max3_f32 v0, v0, v104, v103
	v_max3_f32 v0, v0, v151, v105
	v_max3_f32 v0, v0, v154, v152
	v_max3_f32 v0, v0, v175, v173
	v_max3_f32 v0, v0, v170, v167
	v_max3_f32 v0, v0, v172, v171
	v_max3_f32 v0, v0, v176, v174
	v_max3_f32 v0, v0, v178, v177
	ds_bpermute_b32 v1, v114, v0
	s_waitcnt lgkmcnt(0)
	v_max_f32_e32 v1, v1, v1
	v_max_f32_e32 v0, v0, v1
	ds_bpermute_b32 v1, v115, v0
	s_waitcnt lgkmcnt(0)
	v_max_f32_e32 v1, v1, v1
	v_max_f32_e32 v179, v0, v1
	v_sub_f32_e32 v0, v97, v179
	v_exp_f32_e32 v204, v0
	s_nop 0
	v_pk_mul_f32 v[24:25], v[8:9], v[204:205] op_sel_hi:[1,0]
	v_pk_mul_f32 v[8:9], v[12:13], v[204:205] op_sel_hi:[1,0]
	v_lshl_add_u32 v12, v36, 3, v112
	v_xor_b32_e32 v13, v12, v107
	v_lshl_add_u32 v13, v13, 4, v113
	v_pk_mul_f32 v[26:27], v[10:11], v[204:205] op_sel_hi:[1,0]
	v_pk_mul_f32 v[10:11], v[14:15], v[204:205] op_sel_hi:[1,0]
	v_pk_mul_f32 v[6:7], v[18:19], v[204:205] op_sel_hi:[1,0]
	v_pk_mul_f32 v[4:5], v[16:17], v[204:205] op_sel_hi:[1,0]
	v_pk_mul_f32 v[0:1], v[20:21], v[204:205] op_sel_hi:[1,0]
	ds_read_b128 v[14:17], v13
	ds_read_b128 v[18:21], v13 offset:20480
	ds_read_b128 v[180:183], v13 offset:40960
	ds_read_b128 v[184:187], v13 offset:61440
	v_add_u32_e32 v13, 8, v12
	v_xor_b32_e32 v13, v13, v107
	v_lshl_add_u32 v13, v13, 4, v113
	ds_read_b128 v[188:191], v13
	ds_read_b128 v[192:195], v13 offset:20480
	ds_read_b128 v[196:199], v13 offset:40960
	ds_read_b128 v[200:203], v13 offset:61440
	v_pk_mul_f32 v[2:3], v[22:23], v[204:205] op_sel_hi:[1,0]
	v_sub_f32_e32 v13, v30, v179
	v_exp_f32_e32 v13, v13
	v_sub_f32_e32 v23, v29, v179
	v_exp_f32_e32 v23, v23
	v_fma_f32 v22, v28, v204, v13
	v_sub_f32_e32 v28, v32, v179
	v_exp_f32_e32 v29, v28
	v_sub_f32_e32 v28, v31, v179
	v_exp_f32_e32 v30, v28
	v_sub_f32_e32 v28, v34, v179
	v_exp_f32_e32 v31, v28
	v_sub_f32_e32 v28, v33, v179
	v_exp_f32_e32 v32, v28
	v_sub_f32_e32 v28, v43, v179
	v_add_f32_e32 v22, v23, v22
	v_exp_f32_e32 v33, v28
	v_sub_f32_e32 v28, v41, v179
	v_add_f32_e32 v22, v29, v22
	v_exp_f32_e32 v34, v28
	v_add_f32_e32 v22, v30, v22
	v_add_f32_e32 v22, v31, v22
	v_add_f32_e32 v22, v32, v22
	v_add_f32_e32 v22, v33, v22
	v_cvt_pk_bf16_f32 v28, v13, v23
	v_cvt_pk_bf16_f32 v29, v29, v30
	v_cvt_pk_bf16_f32 v30, v31, v32
	v_cvt_pk_bf16_f32 v31, v33, v34
	v_add_f32_e32 v36, v34, v22
	s_waitcnt lgkmcnt(7)
	v_mfma_f32_16x16x32_bf16 v[14:17], v[14:17], v[28:31], v[24:27]
	s_waitcnt lgkmcnt(6)
	v_mfma_f32_16x16x32_bf16 v[8:11], v[18:21], v[28:31], v[8:11]
	s_waitcnt lgkmcnt(5)
	v_mfma_f32_16x16x32_bf16 v[4:7], v[180:183], v[28:31], v[4:7]
	s_waitcnt lgkmcnt(4)
	v_mfma_f32_16x16x32_bf16 v[0:3], v[184:187], v[28:31], v[0:3]
	v_add_u32_e32 v13, 16, v12
	v_xor_b32_e32 v13, v13, v107
	v_lshl_add_u32 v13, v13, 4, v113
	ds_read_b128 v[18:21], v13
	ds_read_b128 v[22:25], v13 offset:20480
	ds_read_b128 v[26:29], v13 offset:40960
	ds_read_b128 v[30:33], v13 offset:61440
	v_sub_f32_e32 v13, v37, v179
	v_exp_f32_e32 v13, v13
	v_sub_f32_e32 v35, v35, v179
	v_exp_f32_e32 v35, v35
	v_sub_f32_e32 v37, v38, v179
	v_add_f32_e32 v34, v13, v36
	v_sub_f32_e32 v36, v39, v179
	v_exp_f32_e32 v36, v36
	v_exp_f32_e32 v37, v37
	v_sub_f32_e32 v38, v42, v179
	v_exp_f32_e32 v38, v38
	v_sub_f32_e32 v39, v40, v179
	v_add_f32_e32 v34, v35, v34
	v_exp_f32_e32 v39, v39
	v_sub_f32_e32 v40, v51, v179
	v_add_f32_e32 v34, v36, v34
	v_exp_f32_e32 v40, v40
	v_sub_f32_e32 v41, v49, v179
	v_add_f32_e32 v34, v37, v34
	v_exp_f32_e32 v41, v41
	v_add_f32_e32 v34, v38, v34
	v_add_f32_e32 v34, v39, v34
	v_add_f32_e32 v34, v40, v34
	v_add_f32_e32 v42, v41, v34
	v_cvt_pk_bf16_f32 v34, v13, v35
	v_cvt_pk_bf16_f32 v35, v36, v37
	v_cvt_pk_bf16_f32 v36, v38, v39
	v_cvt_pk_bf16_f32 v37, v40, v41
	s_waitcnt lgkmcnt(7)
	s_nop 0
	v_mfma_f32_16x16x32_bf16 v[14:17], v[188:191], v[34:37], v[14:17]
	s_waitcnt lgkmcnt(6)
	v_mfma_f32_16x16x32_bf16 v[8:11], v[192:195], v[34:37], v[8:11]
	s_waitcnt lgkmcnt(5)
	v_mfma_f32_16x16x32_bf16 v[4:7], v[196:199], v[34:37], v[4:7]
	s_waitcnt lgkmcnt(4)
; __device__ __forceinline__ unsigned cvt_pk_bf16(float lo, float hi) { const f32x2 v = (f32x2){lo, hi}; return __builtin_bit_cast(unsigned, __builtin_convertvector(v, bf16v2)); }
; #define AH_LDV(c, bufi) do { const int vaddr = vrow + (((vchunk0 + (c) * vcs + g) ^ qi) << 4); _Pragma("unroll") for (int dt = 0; dt < 4; ++dt) vf[bufi][dt] = *(const LAS bf16x8*)(lds + vaddr + dt * vpitch_dt); } while (0)
; template <bool LOC> ...
;     ...
;     for (int c = 0; c < 8; ++c) {
;         if (c < 7) AH_LDV(c + 1, (c + 1) & 1);
;         __builtin_amdgcn_sched_barrier(0);
;         float pe[8];
; #pragma unroll
;         for (int e = 0; e < 8; ++e) { pe[e] = __builtin_amdgcn_exp2f(s[c][e] - mx); lsum += pe[e]; }
;         u32x4 pw; pw.x = cvt_pk_bf16(pe[0], pe[1]); pw.y = cvt_pk_bf16(pe[2], pe[3]); pw.z = cvt_pk_bf16(pe[4], pe[5]); pw.w = cvt_pk_bf16(pe[6], pe[7]);
;         const bf16x8 pb = __builtin_bit_cast(bf16x8, pw);
; #pragma unroll
;         for (int dt = 0; dt < 4; ++dt) o[dt] = __builtin_amdgcn_mfma_f32_16x16x32_bf16(vf[c & 1][dt], pb, o[dt], 0, 0, 0);
;         __builtin_amdgcn_sched_barrier(0);
;     }
	v_mfma_f32_16x16x32_bf16 v[0:3], v[200:203], v[34:37], v[0:3]
	v_add_u32_e32 v13, 24, v12
	v_xor_b32_e32 v13, v13, v107
	v_lshl_add_u32 v13, v13, 4, v113
	ds_read_b128 v[34:37], v13
	ds_read_b128 v[38:41], v13 offset:20480
	ds_read_b128 v[180:183], v13 offset:40960
	ds_read_b128 v[184:187], v13 offset:61440
	v_sub_f32_e32 v13, v45, v179
	v_exp_f32_e32 v13, v13
	v_sub_f32_e32 v43, v44, v179
	v_exp_f32_e32 v43, v43
	v_sub_f32_e32 v44, v47, v179
	v_exp_f32_e32 v44, v44
	v_sub_f32_e32 v45, v46, v179
	v_exp_f32_e32 v45, v45
	v_sub_f32_e32 v46, v50, v179
	v_add_f32_e32 v42, v13, v42
	v_exp_f32_e32 v46, v46
	v_sub_f32_e32 v47, v48, v179
	v_add_f32_e32 v42, v43, v42
	v_exp_f32_e32 v47, v47
	v_sub_f32_e32 v48, v59, v179
	v_add_f32_e32 v42, v44, v42
	v_exp_f32_e32 v48, v48
	v_sub_f32_e32 v49, v57, v179
	v_add_f32_e32 v42, v45, v42
	v_exp_f32_e32 v49, v49
	v_add_f32_e32 v42, v46, v42
	v_add_f32_e32 v42, v47, v42
	v_add_f32_e32 v42, v48, v42
	v_add_f32_e32 v50, v49, v42
	v_cvt_pk_bf16_f32 v42, v13, v43
	v_cvt_pk_bf16_f32 v43, v44, v45
	v_cvt_pk_bf16_f32 v44, v46, v47
	v_cvt_pk_bf16_f32 v45, v48, v49
	s_waitcnt lgkmcnt(7)
	s_nop 0
	v_mfma_f32_16x16x32_bf16 v[14:17], v[18:21], v[42:45], v[14:17]
	s_waitcnt lgkmcnt(6)
	v_mfma_f32_16x16x32_bf16 v[8:11], v[22:25], v[42:45], v[8:11]
	s_waitcnt lgkmcnt(5)
	v_mfma_f32_16x16x32_bf16 v[4:7], v[26:29], v[42:45], v[4:7]
	s_waitcnt lgkmcnt(4)
	v_mfma_f32_16x16x32_bf16 v[0:3], v[30:33], v[42:45], v[0:3]
	v_add_u32_e32 v13, 32, v12
	v_xor_b32_e32 v13, v13, v107
	v_lshl_add_u32 v13, v13, 4, v113
	ds_read_b128 v[18:21], v13
	ds_read_b128 v[22:25], v13 offset:20480
	ds_read_b128 v[26:29], v13 offset:40960
	ds_read_b128 v[30:33], v13 offset:61440
	v_sub_f32_e32 v13, v53, v179
	v_exp_f32_e32 v13, v13
	v_sub_f32_e32 v43, v52, v179
	v_exp_f32_e32 v43, v43
	v_sub_f32_e32 v44, v55, v179
	v_exp_f32_e32 v44, v44
	v_sub_f32_e32 v45, v54, v179
	v_exp_f32_e32 v45, v45
	v_sub_f32_e32 v46, v58, v179
	v_add_f32_e32 v42, v13, v50
	v_exp_f32_e32 v46, v46
	v_sub_f32_e32 v47, v56, v179
	v_add_f32_e32 v42, v43, v42
	v_exp_f32_e32 v47, v47
	v_sub_f32_e32 v48, v67, v179
	v_add_f32_e32 v42, v44, v42
	v_exp_f32_e32 v48, v48
	v_sub_f32_e32 v49, v65, v179
	v_add_f32_e32 v42, v45, v42
	v_exp_f32_e32 v49, v49
	v_add_f32_e32 v42, v46, v42
	v_add_f32_e32 v42, v47, v42
	v_add_f32_e32 v42, v48, v42
	v_add_f32_e32 v50, v49, v42
	v_cvt_pk_bf16_f32 v42, v13, v43
	v_cvt_pk_bf16_f32 v43, v44, v45
	v_cvt_pk_bf16_f32 v44, v46, v47
	v_cvt_pk_bf16_f32 v45, v48, v49
	s_waitcnt lgkmcnt(7)
	s_nop 0
	v_mfma_f32_16x16x32_bf16 v[14:17], v[34:37], v[42:45], v[14:17]
	s_waitcnt lgkmcnt(6)
	v_mfma_f32_16x16x32_bf16 v[8:11], v[38:41], v[42:45], v[8:11]
	s_waitcnt lgkmcnt(5)
	v_mfma_f32_16x16x32_bf16 v[4:7], v[180:183], v[42:45], v[4:7]
	s_waitcnt lgkmcnt(4)
	v_mfma_f32_16x16x32_bf16 v[0:3], v[184:187], v[42:45], v[0:3]
	v_add_u32_e32 v13, 40, v12
	v_xor_b32_e32 v13, v13, v107
	v_lshl_add_u32 v13, v13, 4, v113
	ds_read_b128 v[34:37], v13
	ds_read_b128 v[38:41], v13 offset:20480
	ds_read_b128 v[42:45], v13 offset:40960
	ds_read_b128 v[46:49], v13 offset:61440
	v_sub_f32_e32 v13, v61, v179
	v_exp_f32_e32 v13, v13
	v_sub_f32_e32 v51, v60, v179
	v_exp_f32_e32 v51, v51
	v_sub_f32_e32 v52, v63, v179
	v_exp_f32_e32 v52, v52
	v_sub_f32_e32 v53, v62, v179
	v_exp_f32_e32 v53, v53
	v_sub_f32_e32 v54, v66, v179
	v_add_f32_e32 v50, v13, v50
	v_exp_f32_e32 v54, v54
	v_sub_f32_e32 v55, v64, v179
	v_add_f32_e32 v50, v51, v50
	v_exp_f32_e32 v55, v55
	v_sub_f32_e32 v56, v102, v179
	v_add_f32_e32 v50, v52, v50
	v_exp_f32_e32 v56, v56
	v_sub_f32_e32 v57, v100, v179
	v_add_f32_e32 v50, v53, v50
	v_exp_f32_e32 v57, v57
	v_add_f32_e32 v50, v54, v50
	v_add_f32_e32 v50, v55, v50
	v_add_f32_e32 v50, v56, v50
	v_add_f32_e32 v58, v57, v50
	v_cvt_pk_bf16_f32 v50, v13, v51
	v_cvt_pk_bf16_f32 v51, v52, v53
	v_cvt_pk_bf16_f32 v52, v54, v55
	v_cvt_pk_bf16_f32 v53, v56, v57
	s_waitcnt lgkmcnt(7)
	s_nop 0
	v_mfma_f32_16x16x32_bf16 v[14:17], v[18:21], v[50:53], v[14:17]
	s_waitcnt lgkmcnt(6)
	v_mfma_f32_16x16x32_bf16 v[8:11], v[22:25], v[50:53], v[8:11]
	s_waitcnt lgkmcnt(5)
	v_mfma_f32_16x16x32_bf16 v[4:7], v[26:29], v[50:53], v[4:7]
	s_waitcnt lgkmcnt(4)
	v_mfma_f32_16x16x32_bf16 v[0:3], v[30:33], v[50:53], v[0:3]
	v_add_u32_e32 v13, 48, v12
	v_xor_b32_e32 v13, v13, v107
	v_lshl_add_u32 v13, v13, 4, v113
	ds_read_b128 v[18:21], v13
	ds_read_b128 v[22:25], v13 offset:20480
	ds_read_b128 v[26:29], v13 offset:40960
	ds_read_b128 v[30:33], v13 offset:61440
	v_sub_f32_e32 v13, v69, v179
	v_exp_f32_e32 v13, v13
	v_sub_f32_e32 v51, v68, v179
	v_exp_f32_e32 v51, v51
	v_sub_f32_e32 v52, v71, v179
	v_exp_f32_e32 v52, v52
	v_sub_f32_e32 v53, v70, v179
	v_exp_f32_e32 v53, v53
	v_sub_f32_e32 v54, v101, v179
	v_add_f32_e32 v50, v13, v58
	v_exp_f32_e32 v54, v54
	v_sub_f32_e32 v55, v99, v179
	v_add_f32_e32 v50, v51, v50
	v_exp_f32_e32 v55, v55
	v_sub_f32_e32 v56, v155, v179
	v_add_f32_e32 v50, v52, v50
	v_exp_f32_e32 v56, v56
	v_sub_f32_e32 v57, v153, v179
	v_add_f32_e32 v50, v53, v50
	v_exp_f32_e32 v57, v57
	v_add_f32_e32 v50, v54, v50
	v_add_f32_e32 v50, v55, v50
	v_add_f32_e32 v50, v56, v50
	v_add_f32_e32 v58, v57, v50
	v_cvt_pk_bf16_f32 v50, v13, v51
	v_cvt_pk_bf16_f32 v51, v52, v53
	v_cvt_pk_bf16_f32 v52, v54, v55
	v_cvt_pk_bf16_f32 v53, v56, v57
	s_waitcnt lgkmcnt(7)
; __device__ __forceinline__ unsigned cvt_pk_bf16(float lo, float hi) { const f32x2 v = (f32x2){lo, hi}; return __builtin_bit_cast(unsigned, __builtin_convertvector(v, bf16v2)); }
; template <bool LOC> ...
;     ...
;         float pe[8];
; #pragma unroll
;         for (int e = 0; e < 8; ++e) { pe[e] = __builtin_amdgcn_exp2f(s[c][e] - mx); lsum += pe[e]; }
;         u32x4 pw; pw.x = cvt_pk_bf16(pe[0], pe[1]); pw.y = cvt_pk_bf16(pe[2], pe[3]); pw.z = cvt_pk_bf16(pe[4], pe[5]); pw.w = cvt_pk_bf16(pe[6], pe[7]);
;         const bf16x8 pb = __builtin_bit_cast(bf16x8, pw);
; #pragma unroll
;         for (int dt = 0; dt < 4; ++dt) o[dt] = __builtin_amdgcn_mfma_f32_16x16x32_bf16(vf[c & 1][dt], pb, o[dt], 0, 0, 0);
;         __builtin_amdgcn_sched_barrier(0);
;     }
;     ...
; }
; __device__ __forceinline__ void attn_store(bf16_t* MIX, int qtok, int h, int g, float lsum, const f32x4 (&o)[4]) {
;     lsum += __shfl_xor(lsum, 16); lsum += __shfl_xor(lsum, 32);
;     const float inv = 1.f / lsum;
;     bf16_t* op = MIX + (size_t)qtok * DM + 512 + h * 64 + 4 * g;
; #pragma unroll
;     for (int dt = 0; dt < 4; ++dt) { u32x2 w; w.x = cvt_pk_bf16(o[dt][0] * inv, o[dt][1] * inv); w.y = cvt_pk_bf16(o[dt][2] * inv, o[dt][3] * inv); *(u32x2*)(op + 16 * dt) = w; }
; }
; __device__ __forceinline__ void phase_mixer(const Params& p, LAS unsigned char* lds, int l, bool with_ctx, int G, int tid, int wave, int lane, int rep_attn, int rep_pool) {
;     ...
;             attn_store(MIX, b * SEQ + r * 64 + 16 * n + qi, h, g, lA, oA);
;         }
;         __syncthreads();
	s_nop 0
	v_mfma_f32_16x16x32_bf16 v[14:17], v[34:37], v[50:53], v[14:17]
	s_waitcnt lgkmcnt(6)
	v_mfma_f32_16x16x32_bf16 v[8:11], v[38:41], v[50:53], v[8:11]
	s_waitcnt lgkmcnt(5)
	v_mfma_f32_16x16x32_bf16 v[4:7], v[42:45], v[50:53], v[4:7]
	s_waitcnt lgkmcnt(4)
	v_mfma_f32_16x16x32_bf16 v[0:3], v[46:49], v[50:53], v[0:3]
	v_add_u32_e32 v12, 56, v12
	v_xor_b32_e32 v12, v12, v107
	v_lshl_add_u32 v12, v12, 4, v113
	ds_read_b128 v[34:37], v12
	ds_read_b128 v[38:41], v12 offset:20480
	ds_read_b128 v[42:45], v12 offset:40960
	ds_read_b128 v[46:49], v12 offset:61440
	v_sub_f32_e32 v12, v104, v179
	v_exp_f32_e32 v12, v12
	v_sub_f32_e32 v50, v103, v179
	v_exp_f32_e32 v50, v50
	v_sub_f32_e32 v51, v151, v179
	v_exp_f32_e32 v51, v51
	v_sub_f32_e32 v52, v105, v179
	v_exp_f32_e32 v52, v52
	v_sub_f32_e32 v53, v154, v179
	v_add_f32_e32 v13, v12, v58
	v_exp_f32_e32 v53, v53
	v_sub_f32_e32 v54, v152, v179
	v_add_f32_e32 v13, v50, v13
	v_exp_f32_e32 v54, v54
	v_sub_f32_e32 v55, v175, v179
	v_sub_f32_e32 v56, v173, v179
	v_add_f32_e32 v13, v51, v13
	v_exp_f32_e32 v55, v55
	v_exp_f32_e32 v56, v56
	v_add_f32_e32 v13, v52, v13
	v_add_f32_e32 v13, v53, v13
	v_add_f32_e32 v13, v54, v13
	v_add_f32_e32 v13, v55, v13
	v_cvt_pk_bf16_f32 v50, v12, v50
	v_cvt_pk_bf16_f32 v51, v51, v52
	v_cvt_pk_bf16_f32 v52, v53, v54
	v_cvt_pk_bf16_f32 v53, v55, v56
	v_add_f32_e32 v57, v56, v13
	s_waitcnt lgkmcnt(7)
	v_mfma_f32_16x16x32_bf16 v[12:15], v[18:21], v[50:53], v[14:17]
	s_waitcnt lgkmcnt(6)
	v_mfma_f32_16x16x32_bf16 v[8:11], v[22:25], v[50:53], v[8:11]
	s_waitcnt lgkmcnt(5)
	v_mfma_f32_16x16x32_bf16 v[4:7], v[26:29], v[50:53], v[4:7]
	s_waitcnt lgkmcnt(4)
	v_mfma_f32_16x16x32_bf16 v[0:3], v[30:33], v[50:53], v[0:3]
	v_sub_f32_e32 v16, v170, v179
	v_exp_f32_e32 v16, v16
	v_sub_f32_e32 v18, v167, v179
	v_exp_f32_e32 v18, v18
	v_sub_f32_e32 v19, v172, v179
	v_exp_f32_e32 v19, v19
	v_sub_f32_e32 v20, v171, v179
	v_exp_f32_e32 v20, v20
	v_sub_f32_e32 v21, v176, v179
	v_add_f32_e32 v17, v16, v57
	v_exp_f32_e32 v21, v21
	v_sub_f32_e32 v22, v174, v179
	v_add_f32_e32 v17, v18, v17
	v_exp_f32_e32 v22, v22
	v_sub_f32_e32 v23, v178, v179
	v_add_f32_e32 v17, v19, v17
	v_exp_f32_e32 v23, v23
	v_sub_f32_e32 v24, v177, v179
	v_add_f32_e32 v17, v20, v17
	v_exp_f32_e32 v24, v24
	v_add_f32_e32 v17, v21, v17
	v_add_f32_e32 v17, v22, v17
	v_add_f32_e32 v17, v23, v17
	v_add_f32_e32 v25, v24, v17
	v_cvt_pk_bf16_f32 v16, v16, v18
	v_cvt_pk_bf16_f32 v17, v19, v20
	v_cvt_pk_bf16_f32 v18, v21, v22
	v_cvt_pk_bf16_f32 v19, v23, v24
	s_waitcnt lgkmcnt(3)
	s_nop 0
	v_mfma_f32_16x16x32_bf16 v[12:15], v[34:37], v[16:19], v[12:15]
	s_waitcnt lgkmcnt(2)
	v_mfma_f32_16x16x32_bf16 v[8:11], v[38:41], v[16:19], v[8:11]
	s_waitcnt lgkmcnt(1)
	v_mfma_f32_16x16x32_bf16 v[4:7], v[42:45], v[16:19], v[4:7]
	s_waitcnt lgkmcnt(0)
	v_mfma_f32_16x16x32_bf16 v[0:3], v[46:49], v[16:19], v[0:3]
	ds_bpermute_b32 v17, v114, v25
	v_or_b32_e32 v16, s62, v108
	v_mov_b32_e32 v99, v157
	s_add_i32 s61, s61, s3
	s_cmpk_gt_i32 s61, 0x7ff
	s_waitcnt lgkmcnt(0)
	v_add_f32_e32 v18, v25, v17
	ds_bpermute_b32 v19, v115, v18
	v_ashrrev_i32_e32 v17, 31, v16
	v_lshlrev_b64 v[16:17], 11, v[16:17]
	v_lshl_add_u64 v[16:17], s[26:27], 0, v[16:17]
	v_lshl_add_u64 v[16:17], v[16:17], 0, s[30:31]
	s_waitcnt lgkmcnt(0)
	v_add_f32_e32 v18, v18, v19
	v_div_scale_f32 v19, s[62:63], v18, v18, 1.0
	v_rcp_f32_e32 v20, v19
	v_div_scale_f32 v21, vcc, 1.0, v18, 1.0
	v_lshl_add_u64 v[16:17], v[16:17], 0, v[98:99]
	v_fma_f32 v22, -v19, v20, 1.0
	v_fmac_f32_e32 v20, v22, v20
	v_mul_f32_e32 v22, v21, v20
	v_fma_f32 v23, -v19, v22, v21
	v_fmac_f32_e32 v22, v23, v20
	v_fma_f32 v19, -v19, v22, v21
	v_div_fmas_f32 v19, v19, v20, v22
	v_div_fixup_f32 v18, v19, v18, 1.0
	v_pk_mul_f32 v[12:13], v[12:13], v[18:19] op_sel_hi:[1,0]
	v_pk_mul_f32 v[14:15], v[14:15], v[18:19] op_sel_hi:[1,0]
	v_pk_mul_f32 v[8:9], v[8:9], v[18:19] op_sel_hi:[1,0]
	v_pk_mul_f32 v[10:11], v[10:11], v[18:19] op_sel_hi:[1,0]
	v_pk_mul_f32 v[4:5], v[4:5], v[18:19] op_sel_hi:[1,0]
	v_pk_mul_f32 v[6:7], v[6:7], v[18:19] op_sel_hi:[1,0]
	v_pk_mul_f32 v[0:1], v[0:1], v[18:19] op_sel_hi:[1,0]
	v_pk_mul_f32 v[2:3], v[2:3], v[18:19] op_sel_hi:[1,0]
	v_cvt_pk_bf16_f32 v12, v12, v13
	v_cvt_pk_bf16_f32 v13, v14, v15
	v_cvt_pk_bf16_f32 v8, v8, v9
	v_cvt_pk_bf16_f32 v9, v10, v11
	v_cvt_pk_bf16_f32 v4, v4, v5
	v_cvt_pk_bf16_f32 v5, v6, v7
	v_cvt_pk_bf16_f32 v0, v0, v1
	v_cvt_pk_bf16_f32 v1, v2, v3
	global_store_dwordx2 v[16:17], v[12:13], off offset:1024
	global_store_dwordx2 v[16:17], v[8:9], off offset:1056
	global_store_dwordx2 v[16:17], v[4:5], off offset:1088
	global_store_dwordx2 v[16:17], v[0:1], off offset:1120
	s_barrier
	s_cbranch_scc1 .LBB0_306
